# v11 plus one static s_setprio 1 for waves 4-7 during the attention phase (reset before the phase barrier)
# speedup vs baseline: 1.0021x; 1.0009x over previous
; __device__ __forceinline__ int lane_now() { int l; asm volatile("v_mbcnt_lo_u32_b32 %0, -1, 0\n\tv_mbcnt_hi_u32_b32 %0, -1, %0" : "=v"(l)); return l; }
; __global__ void __launch_bounds__(NWAVES * 64, 2) fwd_kernel(Args args) {
;     ...
;         using attn_body::bf16; const bf16* q = (const bf16*)QAB; bf16* o = (bf16*)QAB; const bf16* kava = (const bf16*)KAVA; const bf16* kb_ = (const bf16*)KB; const bf16* vb_ = (const bf16*)VB;
;         char* shm = (char*)lds;
;         const int nP = 1024, nS = 2048;
;         const int perP = (nP + G - 1) / G, perS = (nS + G - 1) / G;
;     ...
;         bool nomax;
;         { const int ln_ = lane_now(); float gq = __builtin_fabsf(args.in[4][ln_]), gk = __builtin_fabsf(args.in[5][ln_]);
; #pragma unroll
;           for (int o_ = 1; o_ < 64; o_ <<= 1) { gq = __builtin_fmaxf(gq, __shfl_xor(gq, o_)); gk = __builtin_fmaxf(gk, __shfl_xor(gk, o_)); }
;           nomax = __builtin_amdgcn_readfirstlane((int)(11.78f * gq * gk <= 40.0f)) != 0; }
.LBB0_297:
	s_waitcnt lgkmcnt(0)
	s_barrier
	s_cmp_ge_u32 s84, 0x100
	s_cbranch_scc0 .Lprio_p2_done
	s_setprio 1
.Lprio_p2_done:
	v_mbcnt_lo_u32_b32 v0, -1, 0
	v_mbcnt_hi_u32_b32 v0, -1, v0
	s_abs_i32 s2, s28
	v_ashrrev_i32_e32 v1, 31, v0
	v_lshlrev_b64 v[0:1], 2, v[0:1]
	v_lshl_add_u64 v[2:3], s[44:45], 0, v[0:1]
	global_load_dword v2, v[2:3], off
	v_lshl_add_u64 v[0:1], s[46:47], 0, v[0:1]
	global_load_dword v0, v[0:1], off
	v_mbcnt_hi_u32_b32 v1, -1, v182
	v_and_b32_e32 v3, 64, v1
	v_xor_b32_e32 v4, 1, v1
	v_add_u32_e32 v3, 64, v3
	v_xor_b32_e32 v5, 2, v1
	v_cmp_lt_i32_e32 vcc, v4, v3
	v_xor_b32_e32 v6, 4, v1
	v_cvt_f32_u32_e32 v10, s2
	v_cndmask_b32_e32 v4, v1, v4, vcc
	v_cmp_lt_i32_e32 vcc, v5, v3
	v_xor_b32_e32 v7, 8, v1
	v_xor_b32_e32 v8, 16, v1
	v_cndmask_b32_e32 v5, v1, v5, vcc
	v_cmp_lt_i32_e32 vcc, v6, v3
	v_xor_b32_e32 v9, 32, v1
	v_lshlrev_b32_e32 v4, 2, v4
	v_cndmask_b32_e32 v6, v1, v6, vcc
	v_cmp_lt_i32_e32 vcc, v7, v3
	v_lshlrev_b32_e32 v5, 2, v5
	v_lshlrev_b32_e32 v6, 2, v6
	v_cndmask_b32_e32 v7, v1, v7, vcc
	v_cmp_lt_i32_e32 vcc, v8, v3
	v_lshlrev_b32_e32 v7, 2, v7
	s_sub_i32 s5, 0, s2
	v_cndmask_b32_e32 v8, v1, v8, vcc
	v_cmp_lt_i32_e32 vcc, v9, v3
	v_rcp_iflag_f32_e32 v3, v10
	s_add_i32 s0, s28, 0x3ff
	v_cndmask_b32_e32 v1, v1, v9, vcc
	v_lshlrev_b32_e32 v216, 2, v1
	v_mul_f32_e32 v3, 0x4f7ffffe, v3
	v_cvt_u32_f32_e32 v3, v3
	s_ashr_i32 s4, s0, 31
	s_abs_i32 s0, s0
	v_lshlrev_b32_e32 v215, 2, v8
	v_readfirstlane_b32 s6, v3
	s_mul_i32 s5, s5, s6
	s_mul_hi_u32 s5, s6, s5
	s_add_i32 s6, s6, s5
	s_mul_hi_u32 s5, s0, s6
	s_mul_i32 s7, s5, s2
	s_ashr_i32 s31, s28, 31
	s_sub_i32 s0, s0, s7
	s_add_i32 s1, s28, 0x7ff
	s_xor_b32 s4, s4, s31
	s_add_i32 s8, s5, 1
	s_sub_i32 s7, s0, s2
	s_cmp_ge_u32 s0, s2
	s_cselect_b32 s5, s8, s5
	s_cselect_b32 s0, s7, s0
	s_add_i32 s7, s5, 1
	s_cmp_ge_u32 s0, s2
	s_cselect_b32 s0, s7, s5
	s_ashr_i32 s5, s1, 31
	s_abs_i32 s1, s1
	s_xor_b32 s0, s0, s4
	s_mul_hi_u32 s6, s1, s6
	s_sub_i32 s82, s0, s4
	s_mul_i32 s0, s6, s2
	s_sub_i32 s0, s1, s0
	s_xor_b32 s5, s5, s31
	s_add_i32 s4, s6, 1
	s_sub_i32 s1, s0, s2
	s_cmp_ge_u32 s0, s2
	s_cselect_b32 s4, s4, s6
	s_cselect_b32 s0, s1, s0
	s_add_i32 s1, s4, 1
	s_mov_b32 s3, 0x42200000
	s_cmp_ge_u32 s0, s2
	s_cselect_b32 s0, s1, s4
	s_xor_b32 s0, s0, s5
	s_sub_i32 s2, s0, s5
	s_mov_b32 s37, 0
	s_waitcnt vmcnt(1)
	v_and_b32_e32 v1, 0x7fffffff, v2
	ds_bpermute_b32 v1, v4, v1
	s_waitcnt vmcnt(0)
	v_and_b32_e32 v3, 0x7fffffff, v0
	ds_bpermute_b32 v3, v4, v3
	v_max_f32_e64 v2, |v2|, |v2|
	v_max_f32_e64 v0, |v0|, |v0|
	s_waitcnt lgkmcnt(1)
	v_max_f32_e32 v1, v1, v1
	v_max_f32_e32 v1, v2, v1
	s_waitcnt lgkmcnt(0)
	v_max_f32_e32 v3, v3, v3
	v_max_f32_e32 v0, v0, v3
	ds_bpermute_b32 v2, v5, v1
	ds_bpermute_b32 v3, v5, v0
	s_waitcnt lgkmcnt(1)
	v_max_f32_e32 v2, v2, v2
	s_waitcnt lgkmcnt(0)
	v_max_f32_e32 v3, v3, v3
	v_max_f32_e32 v1, v1, v2
	v_max_f32_e32 v0, v0, v3
	ds_bpermute_b32 v2, v6, v1
	ds_bpermute_b32 v3, v6, v0
	s_waitcnt lgkmcnt(1)
	v_max_f32_e32 v2, v2, v2
	s_waitcnt lgkmcnt(0)
	v_max_f32_e32 v3, v3, v3
	v_max_f32_e32 v1, v1, v2
	v_max_f32_e32 v0, v0, v3
	ds_bpermute_b32 v2, v7, v1
	ds_bpermute_b32 v3, v7, v0
	s_waitcnt lgkmcnt(1)
	v_max_f32_e32 v2, v2, v2
	s_waitcnt lgkmcnt(0)
	v_max_f32_e32 v3, v3, v3
	v_max_f32_e32 v1, v1, v2
	v_max_f32_e32 v0, v0, v3
	ds_bpermute_b32 v2, v215, v1
	ds_bpermute_b32 v3, v215, v0
	s_waitcnt lgkmcnt(1)
	v_max_f32_e32 v2, v2, v2
	s_waitcnt lgkmcnt(0)
	v_max_f32_e32 v3, v3, v3
	v_max_f32_e32 v1, v1, v2
	v_max_f32_e32 v0, v0, v3
	ds_bpermute_b32 v2, v216, v1
	ds_bpermute_b32 v3, v216, v0
	s_waitcnt lgkmcnt(1)
	v_max_f32_e32 v2, v2, v2
	s_waitcnt lgkmcnt(0)
	v_max_f32_e32 v3, v3, v3
	v_max_f32_e32 v1, v1, v2
	v_max_f32_e32 v0, v0, v3
	v_mul_f32_e32 v1, 0x413c7ae1, v1
	v_mul_f32_e32 v0, v0, v1
	v_cmp_ge_f32_e32 vcc, s3, v0
	s_nop 1
	v_cndmask_b32_e64 v0, 0, 1, vcc
	s_nop 0
	v_readfirstlane_b32 s0, v0
	s_bitcmp1_b32 s0, 0
	s_cselect_b64 s[0:1], -1, 0
	s_add_i32 s83, s2, s82
	s_cmp_gt_i32 s83, 0
	s_cbranch_scc0 .LBB0_559
	s_mul_i32 s2, s2, s89
	s_movk_i32 s62, 0x8000
	s_xor_b64 s[38:39], s[0:1], -1
	s_sub_i32 s88, s2, s82
	s_mul_i32 s89, s82, s89
	s_mov_b64 s[0:1], 0
	s_movk_i32 s90, 0x400
	s_mov_b64 s[40:41], 0x8000
	s_mov_b64 s[42:43], 0x100
	v_mov_b32_e32 v0, 0
	s_mov_b64 s[44:45], 0x10000
	s_mov_b64 s[46:47], 0x18000
	s_mov_b64 s[50:51], 0x28000
	s_mov_b64 s[60:61], 0x20000
	s_mov_b32 s63, -1
	s_mov_b32 s91, 0x41000000
	s_mov_b32 s7, 0x20000
	s_mov_b32 s6, 0x10000
	s_mov_b32 s94, 0
	s_mov_b32 s92, 0
	s_branch .LBB0_301

; __device__ __forceinline__ int lane_now() { int l; asm volatile("v_mbcnt_lo_u32_b32 %0, -1, 0\n\tv_mbcnt_hi_u32_b32 %0, -1, %0" : "=v"(l)); return l; }
; __device__ __forceinline__ unsigned xb_ld(unsigned* p)              { return __hip_atomic_load(p, __ATOMIC_RELAXED, __HIP_MEMORY_SCOPE_AGENT); }
; __device__ __forceinline__ void xcd_barrier_complete(unsigned* bar, unsigned x, unsigned& nloc, unsigned& nx) {
;     const unsigned G = gridDim.x * gridDim.y * gridDim.z;
;     unsigned sum, cnt, mine, sp = 0u;
;     for (;;) {
;         sum = 0u; cnt = 0u; mine = 0u;
; #pragma unroll
;         for (unsigned j = 0; j < 16; ++j) { const unsigned c = xb_ld(&bar[XB_XCNT(j)]); sum += c; cnt += (c > 0u) ? 1u : 0u; mine = (j == x) ? c : mine; }
; __device__ __forceinline__ void xcd_barrier(const XcdBarrier& b) {
;     asm volatile("s_waitcnt vmcnt(0)" ::: "memory");
;     __syncthreads();
;     if (b.wave == 0 && lane_now() == 0) {
;         unsigned* bar = b.bar;
;         __builtin_amdgcn_s_waitcnt(0);
;         unsigned nloc = b.st[0], nx = b.st[1];
;         if (nloc == 0u) { xcd_barrier_complete(bar, b.x, nloc, nx); b.st[0] = nloc; b.st[1] = nx; }
.LBB0_559:
	s_waitcnt vmcnt(0)
	v_readlane_b32 s82, v255, 5
	v_readlane_b32 s83, v255, 6
	s_setprio 0
	s_and_b64 vcc, exec, s[82:83]
	s_barrier
	s_cbranch_vccnz .LBB0_613
	v_mbcnt_lo_u32_b32 v0, -1, 0
	v_mbcnt_hi_u32_b32 v0, -1, v0
	s_nop 0
	v_cmp_eq_u32_e32 vcc, 0, v0
	s_and_saveexec_b64 s[0:1], vcc
	s_cbranch_execz .LBB0_612
	s_add_i32 s2, 0, 0x20160
	v_mov_b32_e32 v0, s2
	s_waitcnt vmcnt(0) expcnt(0) lgkmcnt(0)
	ds_read_b32 v2, v0
	s_add_i32 s2, 0, 0x20164
	v_mov_b32_e32 v0, s2
	ds_read_b32 v0, v0
	s_waitcnt lgkmcnt(1)
	v_cmp_ne_u32_e32 vcc, 0, v2
	s_cbranch_vccnz .LBB0_576
	v_readlane_b32 s2, v255, 0
	s_mul_i32 s8, s29, s2
	s_add_u32 s2, s26, 0x300200
	s_addc_u32 s3, s27, 0
	s_add_u32 s4, s26, 0x300400
	s_addc_u32 s5, s27, 0
	s_add_u32 s6, s26, 0x300500
	s_addc_u32 s7, s27, 0
	s_add_u32 s36, s26, 0x300600
	s_addc_u32 s37, s27, 0
	s_add_u32 s38, s26, 0x300700
	s_addc_u32 s39, s27, 0
	s_add_u32 s40, s26, 0x300800
	s_addc_u32 s41, s27, 0
	s_add_u32 s42, s26, 0x300900
	s_addc_u32 s43, s27, 0
	s_add_u32 s44, s26, 0x300a00
	s_addc_u32 s45, s27, 0
	s_add_u32 s46, s26, 0x300b00
	s_addc_u32 s47, s27, 0
	s_add_u32 s48, s26, 0x300c00
	s_addc_u32 s49, s27, 0
	s_add_u32 s50, s26, 0x300d00
	s_addc_u32 s51, s27, 0
	s_add_u32 s60, s26, 0x300e00
	s_addc_u32 s61, s27, 0
	s_add_u32 s62, s26, 0x300f00
	s_addc_u32 s63, s27, 0
	s_add_u32 s64, s26, 0x301000
	s_addc_u32 s65, s27, 0
	s_add_u32 s66, s26, 0x301100
	s_addc_u32 s67, s27, 0
	s_add_u32 s68, s26, 0x301200
	s_addc_u32 s69, s27, 0
	s_add_u32 s70, s26, 0x301300
	s_mul_i32 s8, s8, s28
	s_addc_u32 s71, s27, 0
	s_mov_b32 s9, 1
	v_mov_b32_e32 v16, 0
	s_branch .LBB0_564
